# IDX select bit-descent loop: 2 of every 8 registers count their compare masks on the VALU (v_bcnt_u32_b32 into a uniform VGPR, read back once per pass) instead of s_bcnt1+s_add
# speedup vs baseline: 1.0071x; 1.0071x over previous
; #define PIN8(m) asm volatile("" : "+s"(m[0]), "+s"(m[1]), "+s"(m[2]), "+s"(m[3]), "+s"(m[4]), "+s"(m[5]), "+s"(m[6]), "+s"(m[7]))
; __device__ __forceinline__ void select_query(const float* sc, int* sel, int ce, int lane) {
;     ...
;         const unsigned cand = prefix | (1u << bit);
;         int cnt = 0;
; #pragma unroll
;         for (int g = 0; g < 8; ++g) if (8 * g < nreg) {
;             unsigned long long m[8];
; #pragma unroll
;             for (int j = 0; j < 8; ++j) m[j] = __ballot(key[8 * g + j] >= cand);
;             PIN8(m);
; #pragma unroll
;             for (int j = 0; j < 8; ++j) cnt += __builtin_popcountll(m[j]);
;             asm volatile("" : "+s"(cnt));
;         }
;         if (cnt >= 256) prefix = cand;
;         if (cnt == 256) { exact = true; break; }
;     }
.LBB0_262:
	v_readfirstlane_b32 s1, v67
	s_nop 1
	s_add_i32 s0, s0, s1
	s_cmpk_gt_i32 s0, 0xff
	s_cselect_b64 vcc, -1, 0
	s_cmpk_eq_i32 s0, 0x100
	v_cndmask_b32_e32 v48, v48, v66, vcc
	s_cselect_b64 s[4:5], -1, 0
	v_subrev_co_u32_e32 v65, vcc, 1, v65
	s_or_b64 s[0:1], s[4:5], vcc
	s_andn2_b64 vcc, exec, s[0:1]
	s_cbranch_vccz .LBB0_277
.LBB0_263:
	v_mov_b32_e32 v67, 0
	v_lshlrev_b32_e64 v66, v65, 1
	v_or_b32_e32 v66, v66, v48
	v_cmp_ge_u32_e64 s[0:1], v61, v66
	v_cmp_ge_u32_e64 s[4:5], v31, v66
	v_cmp_ge_u32_e64 s[6:7], v30, v66
	v_cmp_ge_u32_e64 s[8:9], v33, v66
	v_cmp_ge_u32_e64 s[10:11], v32, v66
	v_cmp_ge_u32_e64 s[12:13], v64, v66
	v_cmp_ge_u32_e64 s[14:15], v47, v66
	v_cmp_ge_u32_e64 s[16:17], v46, v66
	s_bcnt1_i32_b64 s0, s[0:1]
	v_bcnt_u32_b32 v67, s4, v67
	v_bcnt_u32_b32 v67, s5, v67
	v_bcnt_u32_b32 v67, s6, v67
	v_bcnt_u32_b32 v67, s7, v67
	s_bcnt1_i32_b64 s1, s[8:9]
	s_add_i32 s0, s0, s1
	s_bcnt1_i32_b64 s1, s[10:11]
	s_add_i32 s0, s0, s1
	s_bcnt1_i32_b64 s1, s[12:13]
	s_add_i32 s0, s0, s1
	s_bcnt1_i32_b64 s1, s[14:15]
	s_add_i32 s0, s0, s1
	s_bcnt1_i32_b64 s1, s[16:17]
	s_add_i32 s0, s0, s1
	s_and_b64 vcc, exec, s[64:65]
	s_cbranch_vccnz .LBB0_270
	v_cmp_ge_u32_e64 s[4:5], v59, v66
	v_cmp_ge_u32_e64 s[6:7], v63, v66
	v_cmp_ge_u32_e64 s[8:9], v41, v66
	v_cmp_ge_u32_e64 s[10:11], v40, v66
	v_cmp_ge_u32_e64 s[12:13], v43, v66
	v_cmp_ge_u32_e64 s[14:15], v42, v66
	v_cmp_ge_u32_e64 s[16:17], v45, v66
	v_cmp_ge_u32_e64 s[18:19], v44, v66
	v_bcnt_u32_b32 v67, s4, v67
	v_bcnt_u32_b32 v67, s5, v67
	v_bcnt_u32_b32 v67, s6, v67
	v_bcnt_u32_b32 v67, s7, v67
	s_bcnt1_i32_b64 s1, s[8:9]
	s_add_i32 s0, s0, s1
	s_bcnt1_i32_b64 s1, s[10:11]
	s_add_i32 s0, s0, s1
	s_bcnt1_i32_b64 s1, s[12:13]
	s_add_i32 s0, s0, s1
	s_bcnt1_i32_b64 s1, s[14:15]
	s_add_i32 s0, s0, s1
	s_bcnt1_i32_b64 s1, s[16:17]
	s_add_i32 s0, s0, s1
	s_bcnt1_i32_b64 s1, s[18:19]
	s_add_i32 s0, s0, s1
	s_and_b64 vcc, exec, s[62:63]
	s_cbranch_vccz .LBB0_271

; #define PIN8(m) asm volatile("" : "+s"(m[0]), "+s"(m[1]), "+s"(m[2]), "+s"(m[3]), "+s"(m[4]), "+s"(m[5]), "+s"(m[6]), "+s"(m[7]))
; __device__ __forceinline__ void select_query(const float* sc, int* sel, int ce, int lane) {
;     ...
;         for (int g = 0; g < 8; ++g) if (8 * g < nreg) {
;             unsigned long long m[8];
; #pragma unroll
;             for (int j = 0; j < 8; ++j) m[j] = __ballot(key[8 * g + j] >= cand);
;             PIN8(m);
; #pragma unroll
;             for (int j = 0; j < 8; ++j) cnt += __builtin_popcountll(m[j]);
;             asm volatile("" : "+s"(cnt));
;         }
.LBB0_266:
	v_cmp_ge_u32_e64 s[4:5], v56, v66
	v_cmp_ge_u32_e64 s[6:7], v60, v66
	v_cmp_ge_u32_e64 s[8:9], v25, v66
	v_cmp_ge_u32_e64 s[10:11], v24, v66
	v_cmp_ge_u32_e64 s[12:13], v27, v66
	v_cmp_ge_u32_e64 s[14:15], v26, v66
	v_cmp_ge_u32_e64 s[16:17], v29, v66
	v_cmp_ge_u32_e64 s[18:19], v28, v66
	v_bcnt_u32_b32 v67, s4, v67
	v_bcnt_u32_b32 v67, s5, v67
	v_bcnt_u32_b32 v67, s6, v67
	v_bcnt_u32_b32 v67, s7, v67
	s_bcnt1_i32_b64 s1, s[8:9]
	s_add_i32 s0, s0, s1
	s_bcnt1_i32_b64 s1, s[10:11]
	s_add_i32 s0, s0, s1
	s_bcnt1_i32_b64 s1, s[12:13]
	s_add_i32 s0, s0, s1
	s_bcnt1_i32_b64 s1, s[14:15]
	s_add_i32 s0, s0, s1
	s_bcnt1_i32_b64 s1, s[16:17]
	s_add_i32 s0, s0, s1
	s_bcnt1_i32_b64 s1, s[18:19]
	s_add_i32 s0, s0, s1
	s_and_b64 vcc, exec, s[58:59]
	s_cbranch_vccz .LBB0_273

; #define PIN8(m) asm volatile("" : "+s"(m[0]), "+s"(m[1]), "+s"(m[2]), "+s"(m[3]), "+s"(m[4]), "+s"(m[5]), "+s"(m[6]), "+s"(m[7]))
; __device__ __forceinline__ void select_query(const float* sc, int* sel, int ce, int lane) {
;     ...
;         for (int g = 0; g < 8; ++g) if (8 * g < nreg) {
;             unsigned long long m[8];
; #pragma unroll
;             for (int j = 0; j < 8; ++j) m[j] = __ballot(key[8 * g + j] >= cand);
;             PIN8(m);
; #pragma unroll
;             for (int j = 0; j < 8; ++j) cnt += __builtin_popcountll(m[j]);
;             asm volatile("" : "+s"(cnt));
;         }
.LBB0_268:
	v_cmp_ge_u32_e64 s[4:5], v52, v66
	v_cmp_ge_u32_e64 s[6:7], v55, v66
	v_cmp_ge_u32_e64 s[8:9], v13, v66
	v_cmp_ge_u32_e64 s[10:11], v12, v66
	v_cmp_ge_u32_e64 s[12:13], v15, v66
	v_cmp_ge_u32_e64 s[14:15], v14, v66
	v_cmp_ge_u32_e64 s[16:17], v17, v66
	v_cmp_ge_u32_e64 s[18:19], v16, v66
	v_bcnt_u32_b32 v67, s4, v67
	v_bcnt_u32_b32 v67, s5, v67
	v_bcnt_u32_b32 v67, s6, v67
	v_bcnt_u32_b32 v67, s7, v67
	s_bcnt1_i32_b64 s1, s[8:9]
	s_add_i32 s0, s0, s1
	s_bcnt1_i32_b64 s1, s[10:11]
	s_add_i32 s0, s0, s1
	s_bcnt1_i32_b64 s1, s[12:13]
	s_add_i32 s0, s0, s1
	s_bcnt1_i32_b64 s1, s[14:15]
	s_add_i32 s0, s0, s1
	s_bcnt1_i32_b64 s1, s[16:17]
	s_add_i32 s0, s0, s1
	s_bcnt1_i32_b64 s1, s[18:19]
	s_add_i32 s0, s0, s1
	s_and_b64 vcc, exec, s[54:55]
	s_cbranch_vccz .LBB0_275

; #define PIN8(m) asm volatile("" : "+s"(m[0]), "+s"(m[1]), "+s"(m[2]), "+s"(m[3]), "+s"(m[4]), "+s"(m[5]), "+s"(m[6]), "+s"(m[7]))
; __device__ __forceinline__ void select_query(const float* sc, int* sel, int ce, int lane) {
;     ...
;         for (int g = 0; g < 8; ++g) if (8 * g < nreg) {
;             unsigned long long m[8];
; #pragma unroll
;             for (int j = 0; j < 8; ++j) m[j] = __ballot(key[8 * g + j] >= cand);
;             PIN8(m);
; #pragma unroll
;             for (int j = 0; j < 8; ++j) cnt += __builtin_popcountll(m[j]);
;             asm volatile("" : "+s"(cnt));
;         }
.LBB0_271:
	v_cmp_ge_u32_e64 s[4:5], v58, v66
	v_cmp_ge_u32_e64 s[6:7], v62, v66
	v_cmp_ge_u32_e64 s[8:9], v35, v66
	v_cmp_ge_u32_e64 s[10:11], v34, v66
	v_cmp_ge_u32_e64 s[12:13], v37, v66
	v_cmp_ge_u32_e64 s[14:15], v36, v66
	v_cmp_ge_u32_e64 s[16:17], v39, v66
	v_cmp_ge_u32_e64 s[18:19], v38, v66
	v_bcnt_u32_b32 v67, s4, v67
	v_bcnt_u32_b32 v67, s5, v67
	v_bcnt_u32_b32 v67, s6, v67
	v_bcnt_u32_b32 v67, s7, v67
	s_bcnt1_i32_b64 s1, s[8:9]
	s_add_i32 s0, s0, s1
	s_bcnt1_i32_b64 s1, s[10:11]
	s_add_i32 s0, s0, s1
	s_bcnt1_i32_b64 s1, s[12:13]
	s_add_i32 s0, s0, s1
	s_bcnt1_i32_b64 s1, s[14:15]
	s_add_i32 s0, s0, s1
	s_bcnt1_i32_b64 s1, s[16:17]
	s_add_i32 s0, s0, s1
	s_bcnt1_i32_b64 s1, s[18:19]
	s_add_i32 s0, s0, s1
	s_and_b64 vcc, exec, s[60:61]
	s_cbranch_vccz .LBB0_266

; #define PIN8(m) asm volatile("" : "+s"(m[0]), "+s"(m[1]), "+s"(m[2]), "+s"(m[3]), "+s"(m[4]), "+s"(m[5]), "+s"(m[6]), "+s"(m[7]))
; __device__ __forceinline__ void select_query(const float* sc, int* sel, int ce, int lane) {
;     ...
;         for (int g = 0; g < 8; ++g) if (8 * g < nreg) {
;             unsigned long long m[8];
; #pragma unroll
;             for (int j = 0; j < 8; ++j) m[j] = __ballot(key[8 * g + j] >= cand);
;             PIN8(m);
; #pragma unroll
;             for (int j = 0; j < 8; ++j) cnt += __builtin_popcountll(m[j]);
;             asm volatile("" : "+s"(cnt));
;         }
.LBB0_273:
	v_cmp_ge_u32_e64 s[4:5], v54, v66
	v_cmp_ge_u32_e64 s[6:7], v57, v66
	v_cmp_ge_u32_e64 s[8:9], v19, v66
	v_cmp_ge_u32_e64 s[10:11], v18, v66
	v_cmp_ge_u32_e64 s[12:13], v21, v66
	v_cmp_ge_u32_e64 s[14:15], v20, v66
	v_cmp_ge_u32_e64 s[16:17], v23, v66
	v_cmp_ge_u32_e64 s[18:19], v22, v66
	v_bcnt_u32_b32 v67, s4, v67
	v_bcnt_u32_b32 v67, s5, v67
	v_bcnt_u32_b32 v67, s6, v67
	v_bcnt_u32_b32 v67, s7, v67
	s_bcnt1_i32_b64 s1, s[8:9]
	s_add_i32 s0, s0, s1
	s_bcnt1_i32_b64 s1, s[10:11]
	s_add_i32 s0, s0, s1
	s_bcnt1_i32_b64 s1, s[12:13]
	s_add_i32 s0, s0, s1
	s_bcnt1_i32_b64 s1, s[14:15]
	s_add_i32 s0, s0, s1
	s_bcnt1_i32_b64 s1, s[16:17]
	s_add_i32 s0, s0, s1
	s_bcnt1_i32_b64 s1, s[18:19]
	s_add_i32 s0, s0, s1
	s_and_b64 vcc, exec, s[56:57]
	s_cbranch_vccz .LBB0_268

; #define PIN8(m) asm volatile("" : "+s"(m[0]), "+s"(m[1]), "+s"(m[2]), "+s"(m[3]), "+s"(m[4]), "+s"(m[5]), "+s"(m[6]), "+s"(m[7]))
; __device__ __forceinline__ void select_query(const float* sc, int* sel, int ce, int lane) {
;     ...
;         for (int g = 0; g < 8; ++g) if (8 * g < nreg) {
;             unsigned long long m[8];
; #pragma unroll
;             for (int j = 0; j < 8; ++j) m[j] = __ballot(key[8 * g + j] >= cand);
;             PIN8(m);
; #pragma unroll
;             for (int j = 0; j < 8; ++j) cnt += __builtin_popcountll(m[j]);
;             asm volatile("" : "+s"(cnt));
;         }
.LBB0_275:
	v_cmp_ge_u32_e64 s[4:5], v50, v66
	v_cmp_ge_u32_e64 s[6:7], v53, v66
	v_cmp_ge_u32_e64 s[8:9], v7, v66
	v_cmp_ge_u32_e64 s[10:11], v6, v66
	v_cmp_ge_u32_e64 s[12:13], v9, v66
	v_cmp_ge_u32_e64 s[14:15], v8, v66
	v_cmp_ge_u32_e64 s[16:17], v11, v66
	v_cmp_ge_u32_e64 s[18:19], v10, v66
	v_bcnt_u32_b32 v67, s4, v67
	v_bcnt_u32_b32 v67, s5, v67
	v_bcnt_u32_b32 v67, s6, v67
	v_bcnt_u32_b32 v67, s7, v67
	s_bcnt1_i32_b64 s1, s[8:9]
	s_add_i32 s0, s0, s1
	s_bcnt1_i32_b64 s1, s[10:11]
	s_add_i32 s0, s0, s1
	s_bcnt1_i32_b64 s1, s[12:13]
	s_add_i32 s0, s0, s1
	s_bcnt1_i32_b64 s1, s[14:15]
	s_add_i32 s0, s0, s1
	s_bcnt1_i32_b64 s1, s[16:17]
	s_add_i32 s0, s0, s1
	s_bcnt1_i32_b64 s1, s[18:19]
	s_add_i32 s0, s0, s1
	s_and_b64 vcc, exec, s[52:53]
	s_cbranch_vccnz .LBB0_262
.LBB0_276:
	v_cmp_ge_u32_e64 s[4:5], v49, v66
	v_cmp_ge_u32_e64 s[6:7], v51, v66
	v_cmp_ge_u32_e64 s[8:9], v5, v66
	v_cmp_ge_u32_e64 s[10:11], v4, v66
	v_cmp_ge_u32_e64 s[12:13], v3, v66
	v_cmp_ge_u32_e64 s[14:15], v2, v66
	v_cmp_ge_u32_e64 s[16:17], v1, v66
	v_cmp_ge_u32_e64 s[18:19], v0, v66
	v_bcnt_u32_b32 v67, s4, v67
	v_bcnt_u32_b32 v67, s5, v67
	v_bcnt_u32_b32 v67, s6, v67
	v_bcnt_u32_b32 v67, s7, v67
	s_bcnt1_i32_b64 s1, s[8:9]
	s_add_i32 s0, s0, s1
	s_bcnt1_i32_b64 s1, s[10:11]
	s_add_i32 s0, s0, s1
	s_bcnt1_i32_b64 s1, s[12:13]
	s_add_i32 s0, s0, s1
	s_bcnt1_i32_b64 s1, s[14:15]
	s_add_i32 s0, s0, s1
	s_bcnt1_i32_b64 s1, s[16:17]
	s_add_i32 s0, s0, s1
	s_bcnt1_i32_b64 s1, s[18:19]
	s_add_i32 s0, s0, s1
	s_branch .LBB0_262
